# CPAIR: attention softmax component of a wave = (wid ^ (wid>>2)) & 1 so the two waves of each SIMD take different components (the heavy epilogue of component 0 then spreads over all four SIMDs), on PEE
# baseline (speedup 1.0000x reference)
.LBB0_985:
	s_and_b32 s42, s6, 7
	s_lshl_b32 s6, s26, 12
	s_and_b32 s27, s41, s40
	s_addk_i32 s6, 0x1000
	s_lshl_b32 s41, s26, 8
	s_and_b64 s[28:29], s[4:5], exec
	s_cselect_b32 s46, s6, s41
	s_lshr_b32 s45, s43, 2
	v_and_or_b32 v4, s45, 48, v152
	s_lshr_b32 s48, s43, 6
	v_lshl_add_u64 v[2:3], s[22:23], 0, v[130:131]
	s_lshl_b32 s6, s42, 8
	v_lshlrev_b32_e32 v4, 11, v4
	v_mov_b32_e32 v5, v131
	v_lshl_add_u64 v[2:3], v[2:3], 0, s[6:7]
	s_lshl_b32 s28, s48, 4
	s_mov_b32 s29, s7
	v_lshl_add_u64 v[4:5], s[24:25], 0, v[4:5]
	v_lshl_add_u64 v[2:3], v[2:3], 0, s[28:29]
	v_lshl_add_u64 v[4:5], v[4:5], 0, s[6:7]
	s_and_b32 s28, s45, 0x3fffffc0
	v_lshl_add_u64 v[4:5], v[4:5], 0, s[28:29]
	s_lshl_b32 s29, s48, 10
	v_mov_b32_e32 v139, v131
	s_add_i32 s48, s29, 0
	s_mov_b32 s49, m0
	s_mov_b32 m0, s48
	s_nop 0
	global_load_lds_dwordx4 v[2:3], off
	s_mov_b32 m0, s49
	v_lshl_add_u64 v[4:5], v[4:5], 0, v[138:139]
	v_lshl_add_u64 v[2:3], v[2:3], 0, s[16:17]
	s_add_i32 s49, s48, 0x2000
	s_mov_b32 s50, m0
	s_mov_b32 m0, s49
	s_nop 0
	global_load_lds_dwordx4 v[2:3], off
	s_mov_b32 m0, s50
	s_lshl_b32 s47, s27, 7
	s_lshr_b32 s27, s43, 7
	s_add_i32 s49, s48, 0xc000
	s_mov_b32 s50, m0
	s_mov_b32 m0, s49
	s_nop 0
	global_load_lds_dwordx4 v[4:5], off
	s_mov_b32 m0, s50
	v_lshl_add_u64 v[2:3], v[4:5], 0, s[16:17]
	s_add_i32 s48, s48, 0xe000
	s_mov_b32 s49, m0
	s_mov_b32 m0, s48
	s_nop 0
	global_load_lds_dwordx4 v[2:3], off
	s_mov_b32 m0, s49
	v_lshl_or_b32 v2, s27, 5, v151
	s_add_i32 s46, s46, s47
	v_add_u32_e32 v142, s46, v2
	v_ashrrev_i32_e32 v143, 31, v142
	v_lshlrev_b64 v[2:3], 11, v[142:143]
	s_lshr_b32 s41, s43, 2
	s_xor_b32 s41, s41, s43
	s_bfe_u32 s41, s41, 0x10006
	v_lshl_add_u64 v[2:3], s[14:15], 0, v[2:3]
	v_lshl_add_u64 v[2:3], v[2:3], 0, s[6:7]
	s_lshl_b32 s46, s41, 7
	s_mov_b32 s47, s7
	v_lshl_add_u64 v[2:3], v[2:3], 0, s[46:47]
	v_mov_b32_e32 v141, v131
	v_lshl_add_u64 v[2:3], v[2:3], 0, v[140:141]
	global_load_dwordx4 v[126:129], v[2:3], off
	global_load_dwordx4 v[122:125], v[2:3], off offset:32
	global_load_dwordx4 v[118:121], v[2:3], off offset:64
	global_load_dwordx4 v[114:117], v[2:3], off offset:96
	s_andn2_b64 vcc, exec, s[4:5]
	s_waitcnt vmcnt(3)
	v_and_b32_e32 v2, 0xffff0000, v126
	v_lshlrev_b32_e32 v3, 16, v126
	v_mul_f32_e32 v2, v2, v2
	v_lshlrev_b32_e32 v4, 16, v127
	v_fmac_f32_e32 v2, v3, v3
	v_and_b32_e32 v5, 0xffff0000, v127
	v_fmac_f32_e32 v2, v4, v4
	v_lshlrev_b32_e32 v6, 16, v128
	v_fmac_f32_e32 v2, v5, v5
	v_and_b32_e32 v7, 0xffff0000, v128
	v_fmac_f32_e32 v2, v6, v6
	v_lshlrev_b32_e32 v8, 16, v129
	v_fmac_f32_e32 v2, v7, v7
	v_and_b32_e32 v9, 0xffff0000, v129
	v_fmac_f32_e32 v2, v8, v8
	s_waitcnt vmcnt(2)
	v_lshlrev_b32_e32 v10, 16, v122
	v_fmac_f32_e32 v2, v9, v9
	v_and_b32_e32 v11, 0xffff0000, v122
	v_fmac_f32_e32 v2, v10, v10
	v_lshlrev_b32_e32 v12, 16, v123
	v_fmac_f32_e32 v2, v11, v11
	v_and_b32_e32 v13, 0xffff0000, v123
	v_fmac_f32_e32 v2, v12, v12
	v_lshlrev_b32_e32 v14, 16, v124
	v_fmac_f32_e32 v2, v13, v13
	v_and_b32_e32 v15, 0xffff0000, v124
	v_fmac_f32_e32 v2, v14, v14
	v_lshlrev_b32_e32 v16, 16, v125
	v_fmac_f32_e32 v2, v15, v15
	v_and_b32_e32 v17, 0xffff0000, v125
	v_fmac_f32_e32 v2, v16, v16
	s_waitcnt vmcnt(1)
	v_lshlrev_b32_e32 v18, 16, v118
	v_fmac_f32_e32 v2, v17, v17
	v_and_b32_e32 v19, 0xffff0000, v118
	v_fmac_f32_e32 v2, v18, v18
	v_lshlrev_b32_e32 v20, 16, v119
	v_fmac_f32_e32 v2, v19, v19
	v_and_b32_e32 v21, 0xffff0000, v119
	v_fmac_f32_e32 v2, v20, v20
	v_lshlrev_b32_e32 v22, 16, v120
	v_fmac_f32_e32 v2, v21, v21
	v_and_b32_e32 v23, 0xffff0000, v120
	v_fmac_f32_e32 v2, v22, v22
	v_lshlrev_b32_e32 v24, 16, v121
	v_fmac_f32_e32 v2, v23, v23
	v_and_b32_e32 v25, 0xffff0000, v121
	v_fmac_f32_e32 v2, v24, v24
	s_waitcnt vmcnt(0)
	v_lshlrev_b32_e32 v26, 16, v114
	v_fmac_f32_e32 v2, v25, v25
	v_and_b32_e32 v27, 0xffff0000, v114
	v_fmac_f32_e32 v2, v26, v26
	v_lshlrev_b32_e32 v28, 16, v115
	v_fmac_f32_e32 v2, v27, v27
	v_and_b32_e32 v29, 0xffff0000, v115
	v_fmac_f32_e32 v2, v28, v28
	v_lshlrev_b32_e32 v30, 16, v116
	v_fmac_f32_e32 v2, v29, v29
	v_and_b32_e32 v31, 0xffff0000, v116
	v_fmac_f32_e32 v2, v30, v30
	v_lshlrev_b32_e32 v32, 16, v117
	v_fmac_f32_e32 v2, v31, v31
	v_fmac_f32_e32 v2, v32, v32
	v_and_b32_e32 v3, 0xffff0000, v117
	v_fmac_f32_e32 v2, v3, v3
	ds_bpermute_b32 v3, v1, v2
	v_mov_b32_e32 v4, v149
	s_cbranch_vccnz .LBB0_987
	s_lshl_b32 s4, s26, 4
	s_lshl_b32 s5, s42, 1
	s_or_b32 s4, s4, s5
	s_or_b32 s4, s4, s41
	s_ashr_i32 s5, s4, 31
	s_lshl_b64 s[4:5], s[4:5], 2
	s_add_u32 s4, s33, s4
	s_addc_u32 s5, s34, s5
	global_load_dword v4, v131, s[4:5]
	s_waitcnt vmcnt(0)
	v_mul_f32_e32 v5, 0x4f800000, v4
	v_cmp_gt_f32_e32 vcc, s36, v4
	s_nop 1
	v_cndmask_b32_e32 v4, v4, v5, vcc
	v_sqrt_f32_e32 v5, v4
	s_nop 0
	v_add_u32_e32 v6, -1, v5
	v_add_u32_e32 v7, 1, v5
	v_fma_f32 v8, -v6, v5, v4
	v_fma_f32 v9, -v7, v5, v4
	v_cmp_ge_f32_e64 s[4:5], 0, v8
	s_nop 1
	v_cndmask_b32_e64 v5, v5, v6, s[4:5]
	v_cmp_lt_f32_e64 s[4:5], 0, v9
	s_nop 1
	v_cndmask_b32_e64 v5, v5, v7, s[4:5]
	v_mul_f32_e32 v6, 0x37800000, v5
	v_cndmask_b32_e32 v5, v5, v6, vcc
	v_cmp_class_f32_e32 vcc, v4, v156
	s_nop 1
	v_cndmask_b32_e32 v4, v5, v4, vcc
	v_mul_f32_e32 v4, 0x3f8147ae, v4
	v_max_f32_e32 v5, v149, v149
	v_max_f32_e32 v4, v5, v4
